# p1 K-loop: two s_nop pads so all four 32-MFMA runs start on an 8-byte boundary (code placement)
# speedup vs baseline: 1.0087x; 1.0087x over previous
; #define PG8_STAGE(bufoff, gbase, voff) do { _Pragma("unroll") for (int _i = 0; _i < 2; ++_i) \
;         __builtin_amdgcn_global_load_lds((const unsigned*)((const char*)(gbase) + (voff)[_i]), (LAS unsigned*)(lds + (bufoff) + ldsw + _i * 8192), 16, 0, 0); } while (0)
; #define PG8_LDA(dst, b, h) do { _Pragma("unroll") for (int m = 0; m < 4; ++m) _Pragma("unroll") for (int k = 0; k < 2; ++k) dst[m][k] = *(const LAS bf16x8*)(lds + PG8_SA(b, h) + aoff + m * 2048 + k * 1024); } while (0)
; #define PG8_LDB(dst, b, h) do { _Pragma("unroll") for (int n = 0; n < 2; ++n) _Pragma("unroll") for (int k = 0; k < 2; ++k) dst[n][k] = *(const LAS bf16x8*)(lds + PG8_SB(b, h) + boff + n * 2048 + k * 1024); } while (0)
; #define PG8_MMA(ai, bj, At, Bt) do { __builtin_amdgcn_s_setprio(1); _Pragma("unroll") for (int m = 0; m < 4; ++m) _Pragma("unroll") for (int n = 0; n < 2; ++n) _Pragma("unroll") for (int k = 0; k < 2; ++k) \
;         acc[ai][bj][m][n] = __builtin_amdgcn_mfma_f32_16x16x32_bf16(Bt[n][k], At[m][k], acc[ai][bj][m][n], 0, 0, 0); __builtin_amdgcn_s_setprio(0); } while (0)
; #define PG8_WAIT_V(n) asm volatile("s_waitcnt vmcnt(" #n ")" ::: "memory")
; #define PG8_WAIT_L(n) asm volatile("s_waitcnt lgkmcnt(" #n ")" ::: "memory")
; #define PG8_BAR __builtin_amdgcn_s_barrier()
; #define PG8_SCHED __builtin_amdgcn_sched_barrier(0)
; template <class Epi>
; DI void gemm_phase(LAS unsigned char* lds, const Gemm g, const StaticOrder& S, const Epi& E) {
;     ...
;             PG8_LDB(B0, 0, 0); PG8_SCHED; PG8_LDA(At, 0, 0); PG8_STAGE(PG8_SA(1, 1), a1 + hstepA, voffA);
;             PG8_WAIT_L(8); PG8_BAR; PG8_WAIT_L(0); PG8_MMA(0, 0, At, B0); PG8_BAR; PG8_SCHED;
;             PG8_LDB(B1, 0, 1); PG8_STAGE(PG8_SB(0, 0), b2, voffB);
;             PG8_BAR; PG8_WAIT_L(0); PG8_MMA(0, 1, At, B1); PG8_BAR;
;             PG8_LDA(At, 0, 1); PG8_STAGE(PG8_SA(0, 0), a2, voffA);
;             PG8_BAR; PG8_WAIT_L(0); PG8_MMA(1, 0, At, B0); PG8_BAR; PG8_SCHED;
;             PG8_STAGE(PG8_SB(0, 1), b2 + hstepB, voffB);
;             PG8_WAIT_V(6); PG8_BAR; PG8_MMA(1, 1, At, B1); PG8_BAR;
.LBB0_113:
	ds_read_b128 v[150:153], v147
	ds_read_b128 v[154:157], v147 offset:1024
	ds_read_b128 v[158:161], v147 offset:2048
	ds_read_b128 v[162:165], v147 offset:3072
	s_add_u32 s0, s52, 0xfff80080
	s_addc_u32 s1, s53, -1
	s_cmp_eq_u32 s83, 28
	s_cselect_b32 s57, s47, s1
	s_cselect_b32 s56, s79, s0
	s_cselect_b32 s55, s17, s82
	s_cselect_b32 s54, s80, s81
	ds_read_b128 v[166:169], v148
	ds_read_b128 v[174:177], v148 offset:1024
	ds_read_b128 v[178:181], v148 offset:2048
	ds_read_b128 v[182:185], v148 offset:3072
	ds_read_b128 v[186:189], v148 offset:4096
	ds_read_b128 v[190:193], v148 offset:5120
	ds_read_b128 v[194:197], v148 offset:6144
	ds_read_b128 v[198:201], v148 offset:7168
	s_waitcnt lgkmcnt(11)
	ds_read_b128 v[202:205], v149
	ds_read_b128 v[206:209], v149 offset:1024
	ds_read_b128 v[210:213], v149 offset:2048
	ds_read_b128 v[216:219], v149 offset:3072
	v_lshl_add_u64 v[238:239], s[52:53], 0, v[136:137]
	s_add_i32 m0, s9, 0xc000
	s_nop 0
	global_load_lds_dwordx4 v[238:239], off
	v_lshl_add_u64 v[238:239], s[52:53], 0, v[138:139]
	s_add_i32 m0, s9, 0xe000
	s_nop 0
	global_load_lds_dwordx4 v[238:239], off
	s_waitcnt lgkmcnt(0)
	s_waitcnt vmcnt(8)
	s_barrier
	v_mfma_f32_16x16x32_bf16 v[124:127], v[150:153], v[166:169], v[124:127]
	v_mfma_f32_16x16x32_bf16 v[120:123], v[158:161], v[166:169], v[120:123]
	v_mfma_f32_16x16x32_bf16 v[116:119], v[150:153], v[178:181], v[116:119]
	v_mfma_f32_16x16x32_bf16 v[112:115], v[158:161], v[178:181], v[112:115]
	v_mfma_f32_16x16x32_bf16 v[100:103], v[150:153], v[186:189], v[100:103]
	v_mfma_f32_16x16x32_bf16 v[96:99], v[158:161], v[186:189], v[96:99]
	v_mfma_f32_16x16x32_bf16 v[84:87], v[150:153], v[194:197], v[84:87]
	v_mfma_f32_16x16x32_bf16 v[80:83], v[158:161], v[194:197], v[80:83]
	v_mfma_f32_16x16x32_bf16 v[124:127], v[154:157], v[174:177], v[124:127]
	v_mfma_f32_16x16x32_bf16 v[120:123], v[162:165], v[174:177], v[120:123]
	v_mfma_f32_16x16x32_bf16 v[116:119], v[154:157], v[182:185], v[116:119]
	v_mfma_f32_16x16x32_bf16 v[112:115], v[162:165], v[182:185], v[112:115]
	v_mfma_f32_16x16x32_bf16 v[100:103], v[154:157], v[190:193], v[100:103]
	v_mfma_f32_16x16x32_bf16 v[96:99], v[162:165], v[190:193], v[96:99]
	v_mfma_f32_16x16x32_bf16 v[84:87], v[154:157], v[198:201], v[84:87]
	v_mfma_f32_16x16x32_bf16 v[80:83], v[162:165], v[198:201], v[80:83]
	v_mfma_f32_16x16x32_bf16 v[108:111], v[202:205], v[166:169], v[108:111]
	v_mfma_f32_16x16x32_bf16 v[104:107], v[210:213], v[166:169], v[104:107]
	v_mfma_f32_16x16x32_bf16 v[92:95], v[202:205], v[178:181], v[92:95]
	v_mfma_f32_16x16x32_bf16 v[88:91], v[210:213], v[178:181], v[88:91]
	v_mfma_f32_16x16x32_bf16 v[76:79], v[202:205], v[186:189], v[76:79]
	v_mfma_f32_16x16x32_bf16 v[72:75], v[210:213], v[186:189], v[72:75]
	v_mfma_f32_16x16x32_bf16 v[68:71], v[202:205], v[194:197], v[68:71]
	v_mfma_f32_16x16x32_bf16 v[64:67], v[210:213], v[194:197], v[64:67]
	v_mfma_f32_16x16x32_bf16 v[108:111], v[206:209], v[174:177], v[108:111]
	v_mfma_f32_16x16x32_bf16 v[104:107], v[216:219], v[174:177], v[104:107]
	v_mfma_f32_16x16x32_bf16 v[92:95], v[206:209], v[182:185], v[92:95]
	v_mfma_f32_16x16x32_bf16 v[88:91], v[216:219], v[182:185], v[88:91]
	v_mfma_f32_16x16x32_bf16 v[76:79], v[206:209], v[190:193], v[76:79]
	v_mfma_f32_16x16x32_bf16 v[72:75], v[216:219], v[190:193], v[72:75]
	v_mfma_f32_16x16x32_bf16 v[68:71], v[206:209], v[198:201], v[68:71]
	v_mfma_f32_16x16x32_bf16 v[64:67], v[216:219], v[198:201], v[64:67]
	s_barrier
	ds_read_b128 v[166:169], v148 offset:16384
	ds_read_b128 v[174:177], v148 offset:17408
	ds_read_b128 v[178:181], v148 offset:18432
	ds_read_b128 v[182:185], v148 offset:19456
	ds_read_b128 v[186:189], v148 offset:20480
	ds_read_b128 v[190:193], v148 offset:21504
	ds_read_b128 v[194:197], v148 offset:22528
	ds_read_b128 v[198:201], v148 offset:23552
	s_add_i32 s0, s75, s58
	v_lshl_add_u64 v[170:171], s[54:55], 0, v[132:133]
	s_mov_b32 m0, s0
	s_nop 0
	global_load_lds_dwordx4 v[170:171], off
	v_lshl_add_u64 v[220:221], s[54:55], 0, v[128:129]
	s_add_i32 m0, s0, 0x2000
	s_nop 0
	global_load_lds_dwordx4 v[220:221], off
	v_lshl_add_u64 v[222:223], s[56:57], 0, v[134:135]
	s_mov_b32 m0, s9
	s_nop 0
	global_load_lds_dwordx4 v[222:223], off
	v_lshl_add_u64 v[224:225], s[56:57], 0, v[130:131]
	s_mov_b32 m0, s61
	s_nop 0
	global_load_lds_dwordx4 v[224:225], off
	s_add_u32 s0, s54, 0x80000
	s_addc_u32 s1, s55, 0
	s_add_i32 s84, s76, s58
	v_lshl_add_u64 v[238:239], s[0:1], 0, v[132:133]
	s_mov_b32 m0, s84
	s_nop 0
	global_load_lds_dwordx4 v[238:239], off
	v_lshl_add_u64 v[238:239], s[0:1], 0, v[128:129]
	s_add_i32 m0, s84, 0x2000
	s_nop 0
	global_load_lds_dwordx4 v[238:239], off
	s_waitcnt lgkmcnt(0)
	s_waitcnt vmcnt(8)
	s_barrier
; #define PG8_STAGE(bufoff, gbase, voff) do { _Pragma("unroll") for (int _i = 0; _i < 2; ++_i) \
;         __builtin_amdgcn_global_load_lds((const unsigned*)((const char*)(gbase) + (voff)[_i]), (LAS unsigned*)(lds + (bufoff) + ldsw + _i * 8192), 16, 0, 0); } while (0)
; #define PG8_LDA(dst, b, h) do { _Pragma("unroll") for (int m = 0; m < 4; ++m) _Pragma("unroll") for (int k = 0; k < 2; ++k) dst[m][k] = *(const LAS bf16x8*)(lds + PG8_SA(b, h) + aoff + m * 2048 + k * 1024); } while (0)
; #define PG8_LDB(dst, b, h) do { _Pragma("unroll") for (int n = 0; n < 2; ++n) _Pragma("unroll") for (int k = 0; k < 2; ++k) dst[n][k] = *(const LAS bf16x8*)(lds + PG8_SB(b, h) + boff + n * 2048 + k * 1024); } while (0)
; #define PG8_MMA(ai, bj, At, Bt) do { __builtin_amdgcn_s_setprio(1); _Pragma("unroll") for (int m = 0; m < 4; ++m) _Pragma("unroll") for (int n = 0; n < 2; ++n) _Pragma("unroll") for (int k = 0; k < 2; ++k) \
;         acc[ai][bj][m][n] = __builtin_amdgcn_mfma_f32_16x16x32_bf16(Bt[n][k], At[m][k], acc[ai][bj][m][n], 0, 0, 0); __builtin_amdgcn_s_setprio(0); } while (0)
; #define PG8_WAIT_V(n) asm volatile("s_waitcnt vmcnt(" #n ")" ::: "memory")
; #define PG8_WAIT_L(n) asm volatile("s_waitcnt lgkmcnt(" #n ")" ::: "memory")
; #define PG8_BAR __builtin_amdgcn_s_barrier()
; #define PG8_SCHED __builtin_amdgcn_sched_barrier(0)
; template <class Epi>
; DI void gemm_phase(LAS unsigned char* lds, const Gemm g, const StaticOrder& S, const Epi& E) {
;     ...
;             PG8_LDA(At, 0, 1); PG8_STAGE(PG8_SA(0, 0), a2, voffA);
;             PG8_BAR; PG8_WAIT_L(0); PG8_MMA(1, 0, At, B0); PG8_BAR; PG8_SCHED;
;             PG8_STAGE(PG8_SB(0, 1), b2 + hstepB, voffB);
;             PG8_WAIT_V(6); PG8_BAR; PG8_MMA(1, 1, At, B1); PG8_BAR;
;             PG8_LDB(B0, 1, 0); PG8_SCHED; PG8_LDA(At, 1, 0); PG8_STAGE(PG8_SA(0, 1), a2 + hstepA, voffA);
;             PG8_WAIT_L(8); PG8_BAR; PG8_WAIT_L(0); PG8_MMA(0, 0, At, B0); PG8_BAR; PG8_SCHED;
	s_nop 0
	v_mfma_f32_16x16x32_bf16 v[60:63], v[150:153], v[166:169], v[60:63]
	v_mfma_f32_16x16x32_bf16 v[56:59], v[158:161], v[166:169], v[56:59]
	v_mfma_f32_16x16x32_bf16 v[52:55], v[150:153], v[178:181], v[52:55]
	v_mfma_f32_16x16x32_bf16 v[48:51], v[158:161], v[178:181], v[48:51]
	v_mfma_f32_16x16x32_bf16 v[36:39], v[150:153], v[186:189], v[36:39]
	v_mfma_f32_16x16x32_bf16 v[32:35], v[158:161], v[186:189], v[32:35]
	v_mfma_f32_16x16x32_bf16 v[20:23], v[150:153], v[194:197], v[20:23]
	v_mfma_f32_16x16x32_bf16 v[16:19], v[158:161], v[194:197], v[16:19]
	v_mfma_f32_16x16x32_bf16 v[60:63], v[154:157], v[174:177], v[60:63]
	v_mfma_f32_16x16x32_bf16 v[56:59], v[162:165], v[174:177], v[56:59]
	v_mfma_f32_16x16x32_bf16 v[52:55], v[154:157], v[182:185], v[52:55]
	v_mfma_f32_16x16x32_bf16 v[48:51], v[162:165], v[182:185], v[48:51]
	v_mfma_f32_16x16x32_bf16 v[36:39], v[154:157], v[190:193], v[36:39]
	v_mfma_f32_16x16x32_bf16 v[32:35], v[162:165], v[190:193], v[32:35]
	v_mfma_f32_16x16x32_bf16 v[20:23], v[154:157], v[198:201], v[20:23]
	v_mfma_f32_16x16x32_bf16 v[16:19], v[162:165], v[198:201], v[16:19]
	v_mfma_f32_16x16x32_bf16 v[44:47], v[202:205], v[166:169], v[44:47]
	v_mfma_f32_16x16x32_bf16 v[40:43], v[210:213], v[166:169], v[40:43]
	v_mfma_f32_16x16x32_bf16 v[28:31], v[202:205], v[178:181], v[28:31]
	v_mfma_f32_16x16x32_bf16 v[24:27], v[210:213], v[178:181], v[24:27]
	v_mfma_f32_16x16x32_bf16 v[12:15], v[202:205], v[186:189], v[12:15]
	v_mfma_f32_16x16x32_bf16 v[8:11], v[210:213], v[186:189], v[8:11]
	v_mfma_f32_16x16x32_bf16 v[4:7], v[202:205], v[194:197], v[4:7]
	v_mfma_f32_16x16x32_bf16 v[0:3], v[210:213], v[194:197], v[0:3]
	v_mfma_f32_16x16x32_bf16 v[44:47], v[206:209], v[174:177], v[44:47]
	v_mfma_f32_16x16x32_bf16 v[40:43], v[216:219], v[174:177], v[40:43]
	v_mfma_f32_16x16x32_bf16 v[28:31], v[206:209], v[182:185], v[28:31]
	v_mfma_f32_16x16x32_bf16 v[24:27], v[216:219], v[182:185], v[24:27]
	v_mfma_f32_16x16x32_bf16 v[12:15], v[206:209], v[190:193], v[12:15]
	v_mfma_f32_16x16x32_bf16 v[8:11], v[216:219], v[190:193], v[8:11]
	v_mfma_f32_16x16x32_bf16 v[4:7], v[206:209], v[198:201], v[4:7]
	v_mfma_f32_16x16x32_bf16 v[0:3], v[216:219], v[198:201], v[0:3]
	s_barrier
	v_add_u32_e32 v252, 0x18000, v145
	v_add_u32_e32 v172, 0x1c000, v145
	ds_read_b128 v[150:153], v252
	ds_read_b128 v[154:157], v252 offset:1024
	ds_read_b128 v[158:161], v252 offset:2048
	ds_read_b128 v[162:165], v252 offset:3072
	ds_read_b128 v[166:169], v148 offset:32768
	ds_read_b128 v[174:177], v148 offset:33792
	ds_read_b128 v[178:181], v148 offset:34816
	ds_read_b128 v[182:185], v148 offset:35840
	ds_read_b128 v[186:189], v148 offset:36864
	ds_read_b128 v[190:193], v148 offset:37888
	ds_read_b128 v[194:197], v148 offset:38912
	ds_read_b128 v[198:201], v148 offset:39936
	s_waitcnt lgkmcnt(11)
	ds_read_b128 v[202:205], v172
	ds_read_b128 v[206:209], v172 offset:1024
	ds_read_b128 v[210:213], v172 offset:2048
	ds_read_b128 v[216:219], v172 offset:3072
	s_add_u32 s0, s56, 0x80000
	s_addc_u32 s1, s57, 0
	v_lshl_add_u64 v[238:239], s[0:1], 0, v[134:135]
	s_mov_b32 m0, s68
	s_nop 0
	global_load_lds_dwordx4 v[238:239], off
	v_lshl_add_u64 v[238:239], s[0:1], 0, v[130:131]
	s_mov_b32 m0, s69
	s_nop 0
	global_load_lds_dwordx4 v[238:239], off
	s_waitcnt lgkmcnt(0)
	s_waitcnt vmcnt(8)
	s_barrier
	v_mfma_f32_16x16x32_bf16 v[124:127], v[150:153], v[166:169], v[124:127]
	v_mfma_f32_16x16x32_bf16 v[120:123], v[158:161], v[166:169], v[120:123]
	v_mfma_f32_16x16x32_bf16 v[116:119], v[150:153], v[178:181], v[116:119]
	v_mfma_f32_16x16x32_bf16 v[112:115], v[158:161], v[178:181], v[112:115]
	v_mfma_f32_16x16x32_bf16 v[100:103], v[150:153], v[186:189], v[100:103]
	v_mfma_f32_16x16x32_bf16 v[96:99], v[158:161], v[186:189], v[96:99]
	v_mfma_f32_16x16x32_bf16 v[84:87], v[150:153], v[194:197], v[84:87]
	v_mfma_f32_16x16x32_bf16 v[80:83], v[158:161], v[194:197], v[80:83]
	v_mfma_f32_16x16x32_bf16 v[124:127], v[154:157], v[174:177], v[124:127]
	v_mfma_f32_16x16x32_bf16 v[120:123], v[162:165], v[174:177], v[120:123]
	v_mfma_f32_16x16x32_bf16 v[116:119], v[154:157], v[182:185], v[116:119]
	v_mfma_f32_16x16x32_bf16 v[112:115], v[162:165], v[182:185], v[112:115]
	v_mfma_f32_16x16x32_bf16 v[100:103], v[154:157], v[190:193], v[100:103]
	v_mfma_f32_16x16x32_bf16 v[96:99], v[162:165], v[190:193], v[96:99]
	v_mfma_f32_16x16x32_bf16 v[84:87], v[154:157], v[198:201], v[84:87]
	v_mfma_f32_16x16x32_bf16 v[80:83], v[162:165], v[198:201], v[80:83]
	v_mfma_f32_16x16x32_bf16 v[108:111], v[202:205], v[166:169], v[108:111]
	v_mfma_f32_16x16x32_bf16 v[104:107], v[210:213], v[166:169], v[104:107]
	v_mfma_f32_16x16x32_bf16 v[92:95], v[202:205], v[178:181], v[92:95]
	v_mfma_f32_16x16x32_bf16 v[88:91], v[210:213], v[178:181], v[88:91]
	v_mfma_f32_16x16x32_bf16 v[76:79], v[202:205], v[186:189], v[76:79]
	v_mfma_f32_16x16x32_bf16 v[72:75], v[210:213], v[186:189], v[72:75]
	v_mfma_f32_16x16x32_bf16 v[68:71], v[202:205], v[194:197], v[68:71]
	v_mfma_f32_16x16x32_bf16 v[64:67], v[210:213], v[194:197], v[64:67]
	v_mfma_f32_16x16x32_bf16 v[108:111], v[206:209], v[174:177], v[108:111]
	v_mfma_f32_16x16x32_bf16 v[104:107], v[216:219], v[174:177], v[104:107]
	v_mfma_f32_16x16x32_bf16 v[92:95], v[206:209], v[182:185], v[92:95]
	v_mfma_f32_16x16x32_bf16 v[88:91], v[216:219], v[182:185], v[88:91]
	v_mfma_f32_16x16x32_bf16 v[76:79], v[206:209], v[190:193], v[76:79]
	v_mfma_f32_16x16x32_bf16 v[72:75], v[216:219], v[190:193], v[72:75]
	v_mfma_f32_16x16x32_bf16 v[68:71], v[206:209], v[198:201], v[68:71]
	v_mfma_f32_16x16x32_bf16 v[64:67], v[216:219], v[198:201], v[64:67]
	s_barrier
; #define PG8_STAGE(bufoff, gbase, voff) do { _Pragma("unroll") for (int _i = 0; _i < 2; ++_i) \
;         __builtin_amdgcn_global_load_lds((const unsigned*)((const char*)(gbase) + (voff)[_i]), (LAS unsigned*)(lds + (bufoff) + ldsw + _i * 8192), 16, 0, 0); } while (0)
; #define PG8_LDA(dst, b, h) do { _Pragma("unroll") for (int m = 0; m < 4; ++m) _Pragma("unroll") for (int k = 0; k < 2; ++k) dst[m][k] = *(const LAS bf16x8*)(lds + PG8_SA(b, h) + aoff + m * 2048 + k * 1024); } while (0)
; #define PG8_LDB(dst, b, h) do { _Pragma("unroll") for (int n = 0; n < 2; ++n) _Pragma("unroll") for (int k = 0; k < 2; ++k) dst[n][k] = *(const LAS bf16x8*)(lds + PG8_SB(b, h) + boff + n * 2048 + k * 1024); } while (0)
; #define PG8_MMA(ai, bj, At, Bt) do { __builtin_amdgcn_s_setprio(1); _Pragma("unroll") for (int m = 0; m < 4; ++m) _Pragma("unroll") for (int n = 0; n < 2; ++n) _Pragma("unroll") for (int k = 0; k < 2; ++k) \
;         acc[ai][bj][m][n] = __builtin_amdgcn_mfma_f32_16x16x32_bf16(Bt[n][k], At[m][k], acc[ai][bj][m][n], 0, 0, 0); __builtin_amdgcn_s_setprio(0); } while (0)
; #define PG8_WAIT_V(n) asm volatile("s_waitcnt vmcnt(" #n ")" ::: "memory")
; #define PG8_WAIT_L(n) asm volatile("s_waitcnt lgkmcnt(" #n ")" ::: "memory")
; #define PG8_BAR __builtin_amdgcn_s_barrier()
; #define PG8_SCHED __builtin_amdgcn_sched_barrier(0)
; template <class Epi>
; DI void gemm_phase(LAS unsigned char* lds, const Gemm g, const StaticOrder& S, const Epi& E) {
;     ...
;             PG8_LDB(B1, 1, 1); PG8_STAGE(PG8_SB(1, 0), b3, voffB);
;             PG8_BAR; PG8_WAIT_L(0); PG8_MMA(0, 1, At, B1); PG8_BAR;
;             PG8_LDA(At, 1, 1); PG8_STAGE(PG8_SA(1, 0), a3, voffA);
;             PG8_BAR; PG8_WAIT_L(0); PG8_MMA(1, 0, At, B0); PG8_BAR; PG8_SCHED;
;             PG8_STAGE(PG8_SB(1, 1), b3 + hstepB, voffB);
;             PG8_WAIT_V(6); PG8_BAR; PG8_MMA(1, 1, At, B1); PG8_BAR;
;         }
	ds_read_b128 v[166:169], v148 offset:49152
	ds_read_b128 v[174:177], v148 offset:50176
	ds_read_b128 v[178:181], v148 offset:51200
	ds_read_b128 v[182:185], v148 offset:52224
	ds_read_b128 v[186:189], v148 offset:53248
	ds_read_b128 v[190:193], v148 offset:54272
	ds_read_b128 v[194:197], v148 offset:55296
	ds_read_b128 v[198:201], v148 offset:56320
	s_add_i32 s0, s58, 0x18000
	v_lshl_add_u64 v[238:239], v[170:171], 0, s[4:5]
	s_mov_b32 m0, s0
	s_nop 0
	global_load_lds_dwordx4 v[238:239], off
	v_lshl_add_u64 v[238:239], v[220:221], 0, s[4:5]
	s_add_i32 m0, s0, 0x2000
	s_nop 0
	global_load_lds_dwordx4 v[238:239], off
	v_lshl_add_u64 v[238:239], v[222:223], 0, s[4:5]
	s_mov_b32 m0, s71
	s_nop 0
	global_load_lds_dwordx4 v[238:239], off
	v_lshl_add_u64 v[238:239], v[224:225], 0, s[4:5]
	s_mov_b32 m0, s72
	s_nop 0
	global_load_lds_dwordx4 v[238:239], off
	s_add_u32 s0, s54, 0x80080
	s_addc_u32 s1, s55, 0
	s_add_i32 s84, s58, 0x1c000
	v_lshl_add_u64 v[238:239], s[0:1], 0, v[132:133]
	s_mov_b32 m0, s84
	s_nop 0
	global_load_lds_dwordx4 v[238:239], off
	v_lshl_add_u64 v[238:239], s[0:1], 0, v[128:129]
	s_add_i32 m0, s84, 0x2000
	s_nop 0
	global_load_lds_dwordx4 v[238:239], off
	s_waitcnt lgkmcnt(0)
	s_waitcnt vmcnt(8)
	s_add_i32 s83, s83, 2
	s_add_u32 s52, s52, 0x100
	s_addc_u32 s53, s53, 0
	s_add_u32 s81, s81, 0x100
	s_addc_u32 s82, s82, 0
	s_cmp_gt_u32 s83, 29
	s_barrier
	s_nop 0
	v_mfma_f32_16x16x32_bf16 v[60:63], v[150:153], v[166:169], v[60:63]
	v_mfma_f32_16x16x32_bf16 v[56:59], v[158:161], v[166:169], v[56:59]
	v_mfma_f32_16x16x32_bf16 v[52:55], v[150:153], v[178:181], v[52:55]
	v_mfma_f32_16x16x32_bf16 v[48:51], v[158:161], v[178:181], v[48:51]
	v_mfma_f32_16x16x32_bf16 v[36:39], v[150:153], v[186:189], v[36:39]
	v_mfma_f32_16x16x32_bf16 v[32:35], v[158:161], v[186:189], v[32:35]
	v_mfma_f32_16x16x32_bf16 v[20:23], v[150:153], v[194:197], v[20:23]
	v_mfma_f32_16x16x32_bf16 v[16:19], v[158:161], v[194:197], v[16:19]
	v_mfma_f32_16x16x32_bf16 v[60:63], v[154:157], v[174:177], v[60:63]
	v_mfma_f32_16x16x32_bf16 v[56:59], v[162:165], v[174:177], v[56:59]
	v_mfma_f32_16x16x32_bf16 v[52:55], v[154:157], v[182:185], v[52:55]
	v_mfma_f32_16x16x32_bf16 v[48:51], v[162:165], v[182:185], v[48:51]
	v_mfma_f32_16x16x32_bf16 v[36:39], v[154:157], v[190:193], v[36:39]
	v_mfma_f32_16x16x32_bf16 v[32:35], v[162:165], v[190:193], v[32:35]
	v_mfma_f32_16x16x32_bf16 v[20:23], v[154:157], v[198:201], v[20:23]
	v_mfma_f32_16x16x32_bf16 v[16:19], v[162:165], v[198:201], v[16:19]
	v_mfma_f32_16x16x32_bf16 v[44:47], v[202:205], v[166:169], v[44:47]
	v_mfma_f32_16x16x32_bf16 v[40:43], v[210:213], v[166:169], v[40:43]
	v_mfma_f32_16x16x32_bf16 v[28:31], v[202:205], v[178:181], v[28:31]
	v_mfma_f32_16x16x32_bf16 v[24:27], v[210:213], v[178:181], v[24:27]
	v_mfma_f32_16x16x32_bf16 v[12:15], v[202:205], v[186:189], v[12:15]
	v_mfma_f32_16x16x32_bf16 v[8:11], v[210:213], v[186:189], v[8:11]
	v_mfma_f32_16x16x32_bf16 v[4:7], v[202:205], v[194:197], v[4:7]
	v_mfma_f32_16x16x32_bf16 v[0:3], v[210:213], v[194:197], v[0:3]
	v_mfma_f32_16x16x32_bf16 v[44:47], v[206:209], v[174:177], v[44:47]
	v_mfma_f32_16x16x32_bf16 v[40:43], v[216:219], v[174:177], v[40:43]
	v_mfma_f32_16x16x32_bf16 v[28:31], v[206:209], v[182:185], v[28:31]
	v_mfma_f32_16x16x32_bf16 v[24:27], v[216:219], v[182:185], v[24:27]
	v_mfma_f32_16x16x32_bf16 v[12:15], v[206:209], v[190:193], v[12:15]
	v_mfma_f32_16x16x32_bf16 v[8:11], v[216:219], v[190:193], v[8:11]
	v_mfma_f32_16x16x32_bf16 v[4:7], v[206:209], v[198:201], v[4:7]
	v_mfma_f32_16x16x32_bf16 v[0:3], v[216:219], v[198:201], v[0:3]
	s_barrier
	s_cbranch_scc0 .LBB0_113
	s_cmpk_gt_u32 s33, 0xff
	s_cbranch_scc1 .Lp1_e0
	s_barrier
